# attention fused path: staging ds_writes of next K/V tile interleaved into QK(sub1) MFMA phase instead of burst at mid-pair
# speedup vs baseline: 1.0165x; 1.0165x over previous
; template <int TYPE>
; __device__ __forceinline__ void attn_item(const Ctx& a, int b, int h, int qt, LAS unsigned char* lds) {
;     ...
; #pragma unroll
;         for (int kk = 0; kk < NKK; ++kk)
; #pragma unroll
;             for (int sub = 0; sub < 2; ++sub)
;                 if (act[sub]) {
; #pragma unroll
;                     for (int kb = 0; kb < 2; ++kb) {
;                         bf16x8 ka = *(const LAS bf16x8*)(Kt + (sub * 64 + kb * 32 + l32) * KLD + kk * 16 + hb * 8);
;                         s[sub][kb] = __builtin_amdgcn_mfma_f32_32x32x16_bf16(ka, Q[kk], s[sub][kb], 0, 0, 0);
;                     }
;                 }
; #pragma unroll
;         for (int sub = 0; sub < 2; ++sub) {
;             if (!act[sub]) continue;
;             const int kt = kp * 2 + sub, kloc = kt - qt * 4;
;             if (kloc >= 0) {
; #pragma unroll
;                 for (int kb = 0; kb < 2; ++kb)
; #pragma unroll
;                     for (int r = 0; r < 16; ++r) { int kabs = kt * 64 + kb * 32 + (r >> 2) * 8 + hb * 4 + (r & 3); if (kabs > qrow) s[sub][kb][r] = -1e30f; }
;             } else if (TYPE == 1) {
;                 if (!((qmask >> (kt >> 2)) & 1u)) {
; #pragma unroll
;                     for (int kb = 0; kb < 2; ++kb)
; #pragma unroll
;                         for (int r = 0; r < 16; ++r) s[sub][kb][r] = -1e30f;
;                 }
;             }
;             float mx = -1e30f;
; #pragma unroll
;             for (int kb = 0; kb < 2; ++kb)
; #pragma unroll
;                 for (int r = 0; r < 16; ++r) mx = fmaxf(mx, s[sub][kb][r]);
;             mx = fmaxf(mx, __shfl_xor(mx, 32));
;             const float delta = mrun - mref;
;             const bool bump = (mx - delta) > 8.f;
;             const bool rare = __builtin_amdgcn_ballot_w64(bump || delta != 0.f) != 0ull;
;             float fpost = 1.f;
;             if (rare) {
;                 const float mnew = bump ? mref + mx : mrun;
;                 const float pre = __builtin_amdgcn_exp2f(delta);
;                 fpost = __builtin_amdgcn_exp2f(mref - mnew);
;                 mrun = mnew;
;                 lrun *= pre;
; #pragma unroll
;                 for (int db = 0; db < 2; ++db)
; #pragma unroll
;                     for (int r = 0; r < 16; ++r) oacc[db][r] *= pre;
;             }
;             float ps = 0.f;
; #pragma unroll
;             for (int kb = 0; kb < 2; ++kb)
; #pragma unroll
.Lat0_loop:
	s_add_u32 s8, s26, 2
	s_cmp_ge_u32 s8, s30
	s_cselect_b32 s57, 1, 0
	s_cmp_eq_u32 s57, 1
	s_cbranch_scc1 .Lat0_gen
	s_cmp_lg_u64 s[36:37], 0
	s_cbranch_scc1 .Lat0_gen
	v_mov_b32 v211, v0
	ds_read_b128 v[146:149], v190 offset:0
	ds_read_b128 v[150:153], v190 offset:6656
	ds_read_b128 v[154:157], v190 offset:32
	ds_read_b128 v[158:161], v190 offset:6688
	ds_read_b128 v[162:165], v190 offset:64
	ds_read_b128 v[166:169], v190 offset:6720
	s_waitcnt lgkmcnt(5)
	v_mfma_f32_32x32x16_bf16 v[48:63], v[146:149], v[112:115], 0
	ds_read_b128 v[170:173], v190 offset:96
	s_waitcnt lgkmcnt(5)
	v_mfma_f32_32x32x16_bf16 v[64:79], v[150:153], v[112:115], 0
	ds_read_b128 v[174:177], v190 offset:6752
	s_waitcnt lgkmcnt(5)
	v_mfma_f32_32x32x16_bf16 v[48:63], v[154:157], v[116:119], v[48:63]
	ds_read_b128 v[146:149], v190 offset:128
	s_waitcnt lgkmcnt(5)
	v_mfma_f32_32x32x16_bf16 v[64:79], v[158:161], v[116:119], v[64:79]
	ds_read_b128 v[150:153], v190 offset:6784
	s_waitcnt lgkmcnt(5)
	v_mfma_f32_32x32x16_bf16 v[48:63], v[162:165], v[120:123], v[48:63]
	ds_read_b128 v[154:157], v190 offset:160
	s_waitcnt lgkmcnt(5)
	v_mfma_f32_32x32x16_bf16 v[64:79], v[166:169], v[120:123], v[64:79]
	ds_read_b128 v[158:161], v190 offset:6816
	s_waitcnt lgkmcnt(5)
	v_mfma_f32_32x32x16_bf16 v[48:63], v[170:173], v[124:127], v[48:63]
	ds_read_b128 v[162:165], v190 offset:13312
	s_waitcnt lgkmcnt(5)
	v_mfma_f32_32x32x16_bf16 v[64:79], v[174:177], v[124:127], v[64:79]
	ds_read_b128 v[166:169], v190 offset:19968
	s_waitcnt lgkmcnt(5)
	v_mfma_f32_32x32x16_bf16 v[48:63], v[146:149], v[128:131], v[48:63]
	ds_read_b128 v[170:173], v190 offset:13344
	s_waitcnt lgkmcnt(5)
	v_mfma_f32_32x32x16_bf16 v[64:79], v[150:153], v[128:131], v[64:79]
	ds_read_b128 v[174:177], v190 offset:20000
	s_waitcnt lgkmcnt(5)
	v_mfma_f32_32x32x16_bf16 v[48:63], v[154:157], v[132:135], v[48:63]
	ds_read_b128 v[146:149], v190 offset:13376
	s_waitcnt lgkmcnt(5)
	v_mfma_f32_32x32x16_bf16 v[64:79], v[158:161], v[132:135], v[64:79]
	ds_read_b128 v[150:153], v190 offset:20032
	s_waitcnt vmcnt(0)
	s_waitcnt lgkmcnt(5)
	v_mfma_f32_32x32x16_bf16 v[80:95], v[162:165], v[112:115], 0
	ds_read_b128 v[154:157], v190 offset:13408
	s_nop 3
	v_max3_f32 v211, v211, v48, v49
	v_exp_f32 v48, v48
	v_exp_f32 v49, v49
	v_max3_f32 v211, v211, v50, v51
	v_exp_f32 v50, v50
	v_exp_f32 v51, v51
	v_add_f32 v188, v48, v49
	v_cvt_pk_bf16_f32 v48, v48, v49
	s_waitcnt lgkmcnt(5)
	v_mfma_f32_32x32x16_bf16 v[96:111], v[166:169], v[112:115], 0
	ds_write_b128 v193, v[2:5]
	ds_read_b128 v[158:161], v190 offset:20064
	v_max3_f32 v211, v211, v52, v53
	v_exp_f32 v52, v52
	v_exp_f32 v53, v53
	v_add_f32 v188, v188, v50
	v_add_f32 v188, v188, v51
	v_cvt_pk_bf16_f32 v49, v50, v51
	v_max3_f32 v211, v211, v54, v55
	v_exp_f32 v54, v54
	s_waitcnt lgkmcnt(6)
	v_mfma_f32_32x32x16_bf16 v[80:95], v[170:173], v[116:119], v[80:95]
	ds_read_b128 v[162:165], v190 offset:13440
	v_exp_f32 v55, v55
	v_add_f32 v188, v188, v52
	v_add_f32 v188, v188, v53
	v_cvt_pk_bf16_f32 v50, v52, v53
	v_max3_f32 v211, v211, v56, v57
	v_exp_f32 v56, v56
	v_exp_f32 v57, v57
	v_add_f32 v188, v188, v54
	s_waitcnt lgkmcnt(6)
	v_mfma_f32_32x32x16_bf16 v[96:111], v[174:177], v[116:119], v[96:111]
	ds_write_b128 v193, v[10:13] offset:13312
	ds_read_b128 v[166:169], v190 offset:20096
	v_add_f32 v188, v188, v55
	v_cvt_pk_bf16_f32 v51, v54, v55
	v_max3_f32 v211, v211, v58, v59
	v_exp_f32 v58, v58
	v_exp_f32 v59, v59
	v_add_f32 v188, v188, v56
	v_add_f32 v188, v188, v57
	v_cvt_pk_bf16_f32 v52, v56, v57
	s_waitcnt lgkmcnt(7)
	v_mfma_f32_32x32x16_bf16 v[80:95], v[146:149], v[120:123], v[80:95]
	ds_read_b128 v[170:173], v190 offset:13472
	v_max3_f32 v211, v211, v60, v61
	v_exp_f32 v60, v60
	v_exp_f32 v61, v61
	v_add_f32 v188, v188, v58
	v_add_f32 v188, v188, v59
	v_cvt_pk_bf16_f32 v53, v58, v59
	v_max3_f32 v211, v211, v62, v63
	v_exp_f32 v62, v62
	s_waitcnt lgkmcnt(7)
	v_mfma_f32_32x32x16_bf16 v[96:111], v[150:153], v[120:123], v[96:111]
	ds_write_b128 v200, v[6:9]
	ds_read_b128 v[174:177], v190 offset:20128
	v_exp_f32 v63, v63
	v_add_f32 v188, v188, v60
	v_add_f32 v188, v188, v61
	v_cvt_pk_bf16_f32 v54, v60, v61
	v_add_f32 v188, v188, v62
	v_add_f32 v188, v188, v63
	v_cvt_pk_bf16_f32 v55, v62, v63
	v_max3_f32 v211, v211, v64, v65
	s_waitcnt lgkmcnt(8)
	v_mfma_f32_32x32x16_bf16 v[80:95], v[154:157], v[124:127], v[80:95]
	ds_read_b64_tr_b16 v[146:147], v191 offset:0
	ds_read_b64_tr_b16 v[148:149], v191 offset:1024
	v_exp_f32 v64, v64
	v_exp_f32 v65, v65
	v_max3_f32 v211, v211, v66, v67
	v_exp_f32 v66, v66
	v_exp_f32 v67, v67
	v_add_f32 v188, v188, v64
	v_add_f32 v188, v188, v65
	v_cvt_pk_bf16_f32 v64, v64, v65
	s_waitcnt lgkmcnt(8)
	v_mfma_f32_32x32x16_bf16 v[96:111], v[158:161], v[124:127], v[96:111]
	ds_write_b128 v200, v[136:139] offset:8192
	ds_read_b64_tr_b16 v[150:151], v192 offset:0
	ds_read_b64_tr_b16 v[152:153], v192 offset:1024
	v_max3_f32 v211, v211, v68, v69
	v_exp_f32 v68, v68
	v_exp_f32 v69, v69
	v_add_f32 v188, v188, v66
	v_add_f32 v188, v188, v67
	v_cvt_pk_bf16_f32 v65, v66, v67
	v_max3_f32 v211, v211, v70, v71
	v_exp_f32 v70, v70
	s_waitcnt lgkmcnt(10)
	v_mfma_f32_32x32x16_bf16 v[80:95], v[162:165], v[128:131], v[80:95]
	ds_read_b64_tr_b16 v[154:155], v191 offset:2048
	ds_read_b64_tr_b16 v[156:157], v191 offset:3072
	v_exp_f32 v71, v71
	v_add_f32 v188, v188, v68
	v_add_f32 v188, v188, v69
	v_cvt_pk_bf16_f32 v66, v68, v69
	v_max3_f32 v211, v211, v72, v73
	v_exp_f32 v72, v72
	v_exp_f32 v73, v73
	v_add_f32 v188, v188, v70
	s_waitcnt lgkmcnt(10)
	v_mfma_f32_32x32x16_bf16 v[96:111], v[166:169], v[128:131], v[96:111]
	ds_write_b128 v201, v[140:143]
	ds_read_b64_tr_b16 v[158:159], v192 offset:2048
	ds_read_b64_tr_b16 v[160:161], v192 offset:3072
	v_add_f32 v188, v188, v71
	v_cvt_pk_bf16_f32 v67, v70, v71
	v_max3_f32 v211, v211, v74, v75
	v_exp_f32 v74, v74
	v_exp_f32 v75, v75
	v_add_f32 v188, v188, v72
	v_add_f32 v188, v188, v73
	v_cvt_pk_bf16_f32 v68, v72, v73
	s_waitcnt lgkmcnt(12)
	v_mfma_f32_32x32x16_bf16 v[80:95], v[170:173], v[132:135], v[80:95]
	ds_read_b64_tr_b16 v[162:163], v191 offset:4096
	ds_read_b64_tr_b16 v[164:165], v191 offset:5120
	v_max3_f32 v211, v211, v76, v77
	v_exp_f32 v76, v76
	v_exp_f32 v77, v77
	v_add_f32 v188, v188, v74
	v_add_f32 v188, v188, v75
	v_cvt_pk_bf16_f32 v69, v74, v75
	v_max3_f32 v211, v211, v78, v79
	v_exp_f32 v78, v78
	s_waitcnt lgkmcnt(12)
	v_mfma_f32_32x32x16_bf16 v[96:111], v[174:177], v[132:135], v[96:111]
	ds_read_b64_tr_b16 v[166:167], v192 offset:4096
	ds_read_b64_tr_b16 v[168:169], v192 offset:5120
	v_exp_f32 v79, v79
	v_add_f32 v188, v188, v76
	v_add_f32 v188, v188, v77
	v_cvt_pk_bf16_f32 v70, v76, v77
	v_add_f32 v188, v188, v78
	v_add_f32 v188, v188, v79
	v_cvt_pk_bf16_f32 v71, v78, v79
	v_add_f32 v206, v206, v188
	s_cmp_eq_u32 s13, 2
	s_cselect_b32 s8, 0x1f800, 0
	s_sub_u32 s8, 0xa800, s8
	s_add_u32 s13, s13, 1
	s_cmp_eq_u32 s13, 3
	s_cselect_b32 s13, 0, s13
	s_waitcnt lgkmcnt(0)
	s_add_u32 s9, s26, 2
	s_cmp_lt_u32 s9, s30
	s_cbranch_scc0 .Lat0_mid1
	global_load_dwordx4 v[2:5], v184, s[52:53]
	global_load_dwordx4 v[6:9], v184, s[52:53] offset:128
	global_load_dwordx4 v[10:13], v185, s[52:53]
	global_load_dwordx4 v[136:139], v185, s[52:53] offset:128
	global_load_dwordx4 v[140:143], v186, s[54:55]
	s_add_u32 s52, s52, 0x70000
	s_addc_u32 s53, s53, 0
	s_add_u32 s54, s54, 0x10000
	s_addc_u32 s55, s55, 0

; template <int TYPE>
; __device__ __forceinline__ void attn_item(const Ctx& a, int b, int h, int qt, LAS unsigned char* lds) {
;     ...
; #pragma unroll
;         for (int kk = 0; kk < NKK; ++kk)
; #pragma unroll
;             for (int sub = 0; sub < 2; ++sub)
;                 if (act[sub]) {
; #pragma unroll
;                     for (int kb = 0; kb < 2; ++kb) {
;                         bf16x8 ka = *(const LAS bf16x8*)(Kt + (sub * 64 + kb * 32 + l32) * KLD + kk * 16 + hb * 8);
;                         s[sub][kb] = __builtin_amdgcn_mfma_f32_32x32x16_bf16(ka, Q[kk], s[sub][kb], 0, 0, 0);
;                     }
;                 }
; #pragma unroll
;         for (int sub = 0; sub < 2; ++sub) {
;             if (!act[sub]) continue;
;             const int kt = kp * 2 + sub, kloc = kt - qt * 4;
;             if (kloc >= 0) {
; #pragma unroll
;                 for (int kb = 0; kb < 2; ++kb)
; #pragma unroll
;                     for (int r = 0; r < 16; ++r) { int kabs = kt * 64 + kb * 32 + (r >> 2) * 8 + hb * 4 + (r & 3); if (kabs > qrow) s[sub][kb][r] = -1e30f; }
;             } else if (TYPE == 1) {
;                 if (!((qmask >> (kt >> 2)) & 1u)) {
; #pragma unroll
;                     for (int kb = 0; kb < 2; ++kb)
; #pragma unroll
;                         for (int r = 0; r < 16; ++r) s[sub][kb][r] = -1e30f;
;                 }
;             }
;             float mx = -1e30f;
; #pragma unroll
;             for (int kb = 0; kb < 2; ++kb)
; #pragma unroll
;                 for (int r = 0; r < 16; ++r) mx = fmaxf(mx, s[sub][kb][r]);
;             mx = fmaxf(mx, __shfl_xor(mx, 32));
;             const float delta = mrun - mref;
;             const bool bump = (mx - delta) > 8.f;
;             const bool rare = __builtin_amdgcn_ballot_w64(bump || delta != 0.f) != 0ull;
;             float fpost = 1.f;
;             if (rare) {
;                 const float mnew = bump ? mref + mx : mrun;
;                 const float pre = __builtin_amdgcn_exp2f(delta);
;                 fpost = __builtin_amdgcn_exp2f(mref - mnew);
;                 mrun = mnew;
;                 lrun *= pre;
; #pragma unroll
;                 for (int db = 0; db < 2; ++db)
; #pragma unroll
;                     for (int r = 0; r < 16; ++r) oacc[db][r] *= pre;
;             }
;             float ps = 0.f;
; #pragma unroll
;             for (int kb = 0; kb < 2; ++kb)
; #pragma unroll
.Lat1_loop:
	s_add_u32 s8, s26, 2
	s_cmp_ge_u32 s8, s30
	s_cselect_b32 s57, 1, 0
	s_lshr_b32 s8, s26, 1
	v_lshrrev_b32 v1, s8, v209
	v_and_b32 v1, 1, v1
	v_sub_u32 v210, 0, v1
	v_cmp_ne_u32_e64 s[38:39], 0, v1
	s_cmp_eq_u32 s57, 1
	s_cbranch_scc1 .Lat1_gen
	s_cmp_eq_u64 s[38:39], 0
	s_cbranch_scc1 .Lat1_skip
	s_cmp_lg_u64 s[36:37], 0
	s_cbranch_scc1 .Lat1_gen
	v_mov_b32 v211, v0
	ds_read_b128 v[146:149], v190 offset:0
	ds_read_b128 v[150:153], v190 offset:4608
	ds_read_b128 v[154:157], v190 offset:32
	ds_read_b128 v[158:161], v190 offset:4640
	ds_read_b128 v[162:165], v190 offset:64
	ds_read_b128 v[166:169], v190 offset:4672
	s_waitcnt lgkmcnt(5)
	v_mfma_f32_32x32x16_bf16 v[48:63], v[146:149], v[112:115], 0
	ds_read_b128 v[170:173], v190 offset:96
	s_waitcnt lgkmcnt(5)
	v_mfma_f32_32x32x16_bf16 v[64:79], v[150:153], v[112:115], 0
	ds_read_b128 v[174:177], v190 offset:4704
	s_waitcnt lgkmcnt(5)
	v_mfma_f32_32x32x16_bf16 v[48:63], v[154:157], v[116:119], v[48:63]
	ds_read_b128 v[146:149], v190 offset:9216
	s_waitcnt lgkmcnt(5)
	v_mfma_f32_32x32x16_bf16 v[64:79], v[158:161], v[116:119], v[64:79]
	ds_read_b128 v[150:153], v190 offset:13824
	s_waitcnt lgkmcnt(5)
	v_mfma_f32_32x32x16_bf16 v[48:63], v[162:165], v[120:123], v[48:63]
	ds_read_b128 v[154:157], v190 offset:9248
	s_waitcnt lgkmcnt(5)
	v_mfma_f32_32x32x16_bf16 v[64:79], v[166:169], v[120:123], v[64:79]
	ds_read_b128 v[158:161], v190 offset:13856
	s_waitcnt lgkmcnt(5)
	v_mfma_f32_32x32x16_bf16 v[48:63], v[170:173], v[124:127], v[48:63]
	ds_read_b128 v[162:165], v190 offset:9280
	s_waitcnt lgkmcnt(5)
	v_mfma_f32_32x32x16_bf16 v[64:79], v[174:177], v[124:127], v[64:79]
	ds_read_b128 v[166:169], v190 offset:13888
	s_waitcnt vmcnt(0)
	s_waitcnt lgkmcnt(5)
	v_mfma_f32_32x32x16_bf16 v[80:95], v[146:149], v[112:115], 0
	ds_read_b128 v[170:173], v190 offset:9312
	s_nop 3
	v_max3_f32 v211, v211, v48, v49
	v_exp_f32 v48, v48
	v_exp_f32 v49, v49
	v_max3_f32 v211, v211, v50, v51
	v_exp_f32 v50, v50
	v_exp_f32 v51, v51
	v_add_f32 v188, v48, v49
	v_cvt_pk_bf16_f32 v48, v48, v49
	v_and_b32 v48, v48, v210
	v_max3_f32 v211, v211, v52, v53
	v_exp_f32 v52, v52
	v_exp_f32 v53, v53
	v_add_f32 v188, v188, v50
	v_add_f32 v188, v188, v51
	s_waitcnt lgkmcnt(5)
	v_mfma_f32_32x32x16_bf16 v[96:111], v[150:153], v[112:115], 0
	ds_write_b128 v193, v[2:5]
	ds_read_b128 v[174:177], v190 offset:13920
	v_cvt_pk_bf16_f32 v49, v50, v51
	v_and_b32 v49, v49, v210
	v_max3_f32 v211, v211, v54, v55
	v_exp_f32 v54, v54
	v_exp_f32 v55, v55
	v_add_f32 v188, v188, v52
	v_add_f32 v188, v188, v53
	v_cvt_pk_bf16_f32 v50, v52, v53
	v_and_b32 v50, v50, v210
	v_max3_f32 v211, v211, v56, v57
	v_exp_f32 v56, v56
	v_exp_f32 v57, v57
	v_add_f32 v188, v188, v54
	v_add_f32 v188, v188, v55
	s_waitcnt lgkmcnt(6)
	v_mfma_f32_32x32x16_bf16 v[80:95], v[154:157], v[116:119], v[80:95]
	ds_read_b64_tr_b16 v[146:147], v191 offset:0
	ds_read_b64_tr_b16 v[148:149], v191 offset:1024
	v_cvt_pk_bf16_f32 v51, v54, v55
	v_and_b32 v51, v51, v210
	v_max3_f32 v211, v211, v58, v59
	v_exp_f32 v58, v58
	v_exp_f32 v59, v59
	v_add_f32 v188, v188, v56
	v_add_f32 v188, v188, v57
	v_cvt_pk_bf16_f32 v52, v56, v57
	v_and_b32 v52, v52, v210
	v_max3_f32 v211, v211, v60, v61
	v_exp_f32 v60, v60
	v_exp_f32 v61, v61
	v_add_f32 v188, v188, v58
	v_add_f32 v188, v188, v59
	s_waitcnt lgkmcnt(7)
	v_mfma_f32_32x32x16_bf16 v[96:111], v[158:161], v[116:119], v[96:111]
	ds_write_b128 v193, v[10:13] offset:9216
	ds_read_b64_tr_b16 v[150:151], v192 offset:0
	ds_read_b64_tr_b16 v[152:153], v192 offset:1024
	v_cvt_pk_bf16_f32 v53, v58, v59
	v_and_b32 v53, v53, v210
	v_max3_f32 v211, v211, v62, v63
	v_exp_f32 v62, v62
	v_exp_f32 v63, v63
	v_add_f32 v188, v188, v60
	v_add_f32 v188, v188, v61
	v_cvt_pk_bf16_f32 v54, v60, v61
	v_and_b32 v54, v54, v210
	v_add_f32 v188, v188, v62
	v_add_f32 v188, v188, v63
	v_cvt_pk_bf16_f32 v55, v62, v63
	v_and_b32 v55, v55, v210
	v_max3_f32 v211, v211, v64, v65
	s_waitcnt lgkmcnt(9)
	v_mfma_f32_32x32x16_bf16 v[80:95], v[162:165], v[120:123], v[80:95]
	ds_read_b64_tr_b16 v[154:155], v191 offset:2048
	ds_read_b64_tr_b16 v[156:157], v191 offset:3072
	v_exp_f32 v64, v64
	v_exp_f32 v65, v65
	v_max3_f32 v211, v211, v66, v67
	v_exp_f32 v66, v66
	v_exp_f32 v67, v67
	v_add_f32 v188, v188, v64
	v_add_f32 v188, v188, v65
	v_cvt_pk_bf16_f32 v64, v64, v65
	v_and_b32 v64, v64, v210
	v_max3_f32 v211, v211, v68, v69
	v_exp_f32 v68, v68
	v_exp_f32 v69, v69
	v_add_f32 v188, v188, v66
	v_add_f32 v188, v188, v67
	s_waitcnt lgkmcnt(10)
	v_mfma_f32_32x32x16_bf16 v[96:111], v[166:169], v[120:123], v[96:111]
	ds_write_b128 v200, v[6:9]
	ds_read_b64_tr_b16 v[158:159], v192 offset:2048
	ds_read_b64_tr_b16 v[160:161], v192 offset:3072
	v_cvt_pk_bf16_f32 v65, v66, v67
	v_and_b32 v65, v65, v210
	v_max3_f32 v211, v211, v70, v71
	v_exp_f32 v70, v70
	v_exp_f32 v71, v71
	v_add_f32 v188, v188, v68
	v_add_f32 v188, v188, v69
	v_cvt_pk_bf16_f32 v66, v68, v69
	v_and_b32 v66, v66, v210
	v_max3_f32 v211, v211, v72, v73
	v_exp_f32 v72, v72
	v_exp_f32 v73, v73
	v_add_f32 v188, v188, v70
	v_add_f32 v188, v188, v71
	s_waitcnt lgkmcnt(12)
	v_mfma_f32_32x32x16_bf16 v[80:95], v[170:173], v[124:127], v[80:95]
	ds_read_b64_tr_b16 v[162:163], v191 offset:4096
	ds_read_b64_tr_b16 v[164:165], v191 offset:5120
	v_cvt_pk_bf16_f32 v67, v70, v71
	v_and_b32 v67, v67, v210
	v_max3_f32 v211, v211, v74, v75
	v_exp_f32 v74, v74
	v_exp_f32 v75, v75
	v_add_f32 v188, v188, v72
	v_add_f32 v188, v188, v73
	v_cvt_pk_bf16_f32 v68, v72, v73
	v_and_b32 v68, v68, v210
	v_max3_f32 v211, v211, v76, v77
	v_exp_f32 v76, v76
	v_exp_f32 v77, v77
	v_add_f32 v188, v188, v74
	v_add_f32 v188, v188, v75
	s_waitcnt lgkmcnt(12)
	v_mfma_f32_32x32x16_bf16 v[96:111], v[174:177], v[124:127], v[96:111]
	ds_write_b128 v200, v[136:139] offset:8192
	ds_read_b64_tr_b16 v[166:167], v192 offset:4096
	ds_read_b64_tr_b16 v[168:169], v192 offset:5120
	v_cvt_pk_bf16_f32 v69, v74, v75
	v_and_b32 v69, v69, v210
	v_max3_f32 v211, v211, v78, v79
	v_exp_f32 v78, v78
	v_exp_f32 v79, v79
	v_add_f32 v188, v188, v76
	v_add_f32 v188, v188, v77
	v_cvt_pk_bf16_f32 v70, v76, v77
	v_and_b32 v70, v70, v210
	v_add_f32 v188, v188, v78
	v_add_f32 v188, v188, v79
	v_cvt_pk_bf16_f32 v71, v78, v79
	v_and_b32 v71, v71, v210
	v_and_b32 v188, v188, v210
	v_add_f32 v206, v206, v188
	s_cmp_eq_u32 s13, 2
	s_cselect_b32 s8, 0x19800, 0
	s_sub_u32 s8, 0x8800, s8
	s_add_u32 s13, s13, 1
	s_cmp_eq_u32 s13, 3
	s_cselect_b32 s13, 0, s13
	s_waitcnt lgkmcnt(0)
	s_add_u32 s9, s26, 2
	s_cmp_lt_u32 s9, s30
	s_cbranch_scc0 .Lat1_mid3
	global_load_dwordx4 v[2:5], v184, s[52:53]
	global_load_dwordx4 v[6:9], v184, s[52:53] offset:1024
	global_load_dwordx4 v[10:13], v185, s[52:53]
	global_load_dwordx4 v[136:139], v185, s[52:53] offset:1024
	s_add_u32 s52, s52, 0x100000
	s_addc_u32 s53, s53, 0
